# grid-barrier poll pacing: s_sleep 3 instead of s_sleep 1 between polls of the cross-XCC counter
# baseline (speedup 1.0000x reference)
; __global__ void __launch_bounds__(512, 2) mega(P p_arg) {
;     ...
;         if (code & 128) { if (si + 1 < nseq) cg::this_grid().sync(); }
.Lmy_poll:
	global_load_dword v2, v1, s[10:11] offset:3968 sc1
	s_waitcnt vmcnt(0)
	v_readfirstlane_b32 s7, v2
	s_cmp_ge_u32 s7, s5
	s_cbranch_scc1 .Lmy_released
	s_sleep 3
	s_branch .Lmy_poll
